# K-split-11 units mapped so that units sharing an A slice sit on one XCD (L2 reuse); plain stores for converted weights
# speedup vs baseline: 1.0208x; 1.0012x over previous
.LBB0_778:
	s_cmpk_lg_i32 s12, 0x1600
	s_cbranch_scc1 .Lks_four
	s_cmpk_lg_i32 s38, 0x100
	s_cbranch_scc1 .Lks_four
	s_and_b32 s4, s2, 7
	s_lshr_b32 s5, s2, 3
	s_cmp_lt_u32 s5, 16
	s_cbranch_scc1 .Lks_map_a
	s_sub_u32 s5, s5, 16
	s_lshl_b32 s5, s5, 3
	s_add_u32 s5, s5, s4
	s_lshr_b32 s4, s5, 4
	s_add_u32 s4, s4, 8
	s_and_b32 s5, s5, 15
.Lks_map_a:
	v_writelane_b32 v248, s4, 24
	s_lshl_b32 s4, s4, 3
	v_writelane_b32 v248, s5, 23
	s_lshr_b32 s5, s5, 1
	s_add_u32 s4, s4, s5
	v_writelane_b32 v248, s5, 26
	v_writelane_b32 v248, s4, 22
	v_readlane_b32 s4, v248, 23
	s_and_b32 s4, s4, 1
	v_writelane_b32 v248, s4, 23
	s_mov_b32 s4, 0
	v_writelane_b32 v248, s4, 25
	v_writelane_b32 v248, s4, 27
	s_mov_b32 s4, 1
	v_writelane_b32 v248, s4, 28
	s_cmpk_lt_u32 s2, 0xb0
	s_cselect_b64 s[4:5], -1, 0
	s_branch .Lks_done
